# sample retention units: no full vmcnt drain at the item start (the q/k/v wait covers older stores in order)
# baseline (speedup 1.0000x reference)
; __device__ void sample_ret_unit(const Params& p, int l, int unit, LAS unsigned char* lds, const int tid_in) {
;     const int tid = launder(tid_in);
;     const int wid = tid >> 6, lane = tid & 63;
;     const int b = unit >> 3, h = unit & 7, r0 = b * 8;
;     const float lg = lg2gamma(h);
;     LAS float* sq = (LAS float*)lds; LAS float* sk = sq + 2048; LAS float* sv = sk + 2048; LAS float* sqT = sv + 2048; LAS float* skdT = sqT + 2048; LAS float* sc = skdT + 2048; LAS float* red = (LAS float*)(lds + 49152);
;     const bf16_t* zb = (const bf16_t*)(pws(p) + OFF_ZB);
;     { const int i = tid >> 6, d = (tid & 63) * 4; const bf16_t* zr = zb + (size_t)(r0 + i) * ZW + h * 256 + d;
;         const u32x2 a = *(const u32x2*)(zr + ZC_Q), kk = *(const u32x2*)(zr + ZC_K), vv = *(const u32x2*)(zr + ZC_V);
;         const float qf[4] = {bf_lo(a.x), bf_hi(a.x), bf_lo(a.y), bf_hi(a.y)}, kf[4] = {bf_lo(kk.x), bf_hi(kk.x), bf_lo(kk.y), bf_hi(kk.y)};
;         const float dk = exp2f(lg * (float)(7 - i));
;         *(LAS f32x4*)(sq + i * 256 + d) = (f32x4){qf[0], qf[1], qf[2], qf[3]};
;         *(LAS f32x4*)(sk + i * 256 + d) = (f32x4){kf[0], kf[1], kf[2], kf[3]};
;         *(LAS f32x4*)(sv + i * 256 + d) = (f32x4){bf_lo(vv.x), bf_hi(vv.x), bf_lo(vv.y), bf_hi(vv.y)};
; #pragma unroll
;         for (int j = 0; j < 4; ++j) { sqT[(d + j) * 8 + i] = qf[j]; skdT[(d + j) * 8 + i] = kf[j] * dk; } }
;     __syncthreads();
;     { const int i = wid; const f32x4 qv = *(const LAS f32x4*)(sq + i * 256 + lane * 4);
;         for (int j = 0; j < 8; ++j) { const f32x4 kv = *(const LAS f32x4*)(sk + j * 256 + lane * 4);
;             float s = wave_sum(qv[0] * kv[0] + qv[1] * kv[1] + qv[2] * kv[2] + qv[3] * kv[3]);
;             if (lane == 0) sc[i * 8 + j] = j <= i ? s * exp2f(lg * (float)(i - j)) : 0.f; } }
;     const int e4 = lane * 4;
;     f32x4 vv[8], oacc[8];
; #pragma unroll
;     for (int j = 0; j < 8; ++j) { vv[j] = *(const LAS f32x4*)(sv + j * 256 + e4); oacc[j] = (f32x4){0.f, 0.f, 0.f, 0.f}; }
;     const float g8 = exp2f(lg * 8.0f);
;     const size_t sbase = (((size_t)l * 128 + b) * 8 + h) * 65536;
;     const float* Sin = p.state_ret + sbase; float* Sout = pout(p) + O_RS + sbase;
;     f32x4 S4[8], N4[8];
; #pragma unroll
;     for (int u = 0; u < 8; ++u) S4[u] = __builtin_nontemporal_load((const f32x4*)(Sin + (size_t)(wid * 32 + u) * 256 + e4));
.LBB0_522:
	s_and_b64 vcc, exec, s[0:1]
	s_cbranch_vccz .LBB0_544
	v_mov_b32_e32 v0, v244
	s_and_b32 s9, s38, 7
	v_ashrrev_i32_e32 v138, 6, v0
	v_and_b32_e32 v139, 63, v0
	v_cvt_f32_ubyte0_e32 v0, s9
	v_sub_f32_e32 v0, 0xc0a00000, v0
	v_cmp_gt_f32_e32 vcc, s75, v0
	s_and_b32 s8, s38, -8
	s_and_b64 s[0:1], vcc, exec
	v_cndmask_b32_e32 v2, 0, v237, vcc
	v_add_f32_e32 v0, v0, v2
	v_exp_f32_e32 v0, v0
	s_cselect_b32 s0, 0xffffffc0, 0
	s_lshl_b32 s90, s9, 9
	v_ldexp_f32 v10, v0, s0
	v_sub_f32_e32 v0, 1.0, v10
	v_add_f32_e32 v2, -1.0, v0
	v_sub_f32_e32 v3, v2, v0
	v_add_f32_e32 v3, 1.0, v3
	v_sub_f32_e64 v2, -v10, v2
	v_add_f32_e32 v4, v2, v3
	v_frexp_mant_f32_e32 v5, v0
	v_cvt_f64_f32_e32 v[2:3], v0
	s_mov_b32 s0, 0x3f2aaaab
	v_frexp_exp_i32_f64_e32 v2, v[2:3]
	v_cmp_gt_f32_e32 vcc, s0, v5
	v_readlane_b32 s0, v253, 19
	v_readlane_b32 s1, v253, 20
	v_subbrev_co_u32_e32 v11, vcc, 0, v2, vcc
	v_sub_u32_e32 v2, 0, v11
	v_ldexp_f32 v0, v0, v2
	v_add_f32_e32 v3, -1.0, v0
	v_add_f32_e32 v6, 1.0, v0
	v_ldexp_f32 v2, v4, v2
	v_add_f32_e32 v4, 1.0, v3
	v_add_f32_e32 v7, -1.0, v6
	v_sub_f32_e32 v4, v0, v4
	v_sub_f32_e32 v0, v0, v7
	v_add_f32_e32 v0, v2, v0
	v_add_f32_e32 v12, v6, v0
	v_rcp_f32_e32 v14, v12
	v_add_f32_e32 v4, v2, v4
	v_add_f32_e32 v5, v3, v4
	v_sub_f32_e32 v2, v12, v6
	v_mul_f32_e32 v15, v5, v14
	v_sub_f32_e32 v13, v0, v2
	v_mul_f32_e32 v0, v12, v15
	v_fma_f32 v9, v15, v12, -v0
	v_fmac_f32_e32 v9, v15, v13
	v_add_f32_e32 v2, v0, v9
	v_sub_f32_e32 v17, v5, v2
	v_sub_f32_e32 v3, v5, v3
	v_sub_f32_e32 v16, v2, v0
	v_sub_f32_e32 v0, v5, v17
	v_sub_f32_e32 v8, v4, v3
	v_sub_f32_e32 v18, v0, v2
	v_add_u32_e32 v0, s8, v138
	v_mov_b64_e32 v[2:3], s[0:1]
	v_mad_i64_i32 v[140:141], s[0:1], v0, s74, v[2:3]
	v_lshl_add_u64 v[2:3], v[140:141], 0, s[90:91]
	v_lshlrev_b32_e32 v0, 3, v139
	v_lshl_add_u64 v[2:3], v[2:3], 0, v[0:1]
	s_movk_i32 s0, 0x2000
	v_add_f32_e32 v0, v8, v18
	v_sub_f32_e32 v8, v16, v9
	v_add_co_u32_e32 v4, vcc, s0, v2
	v_add_f32_e32 v0, v8, v0
	s_nop 0
	v_addc_co_u32_e32 v5, vcc, 0, v3, vcc
	v_add_f32_e32 v16, v17, v0
	global_load_dwordx2 v[6:7], v[4:5], off offset:-4096
	global_load_dwordx2 v[8:9], v[4:5], off
	v_mul_f32_e32 v18, v14, v16
	v_mul_f32_e32 v4, v12, v18
	v_fma_f32 v5, v18, v12, -v4
	v_fmac_f32_e32 v5, v18, v13
	v_sub_f32_e32 v12, v17, v16
	v_add_f32_e32 v0, v0, v12
	v_add_f32_e32 v12, v4, v5
	v_sub_f32_e32 v17, v16, v12
	s_movk_i32 s0, 0x3000
	v_sub_f32_e32 v13, v16, v17
	v_add_co_u32_e32 v2, vcc, s0, v2
	v_sub_f32_e32 v4, v12, v4
	v_sub_f32_e32 v12, v13, v12
	v_addc_co_u32_e32 v3, vcc, 0, v3, vcc
	v_add_f32_e32 v0, v0, v12
	global_load_dwordx2 v[12:13], v[2:3], off
	s_ashr_i32 s12, s38, 3
	s_ashr_i32 s13, s12, 31
	s_lshl_b64 s[12:13], s[12:13], 3
	s_add_u32 s12, s12, s26
	s_addc_u32 s13, s13, s27
	s_or_b32 s12, s12, s9
	s_lshl_b64 s[12:13], s[12:13], 18
	s_add_u32 s12, s50, s12
	s_addc_u32 s13, s51, s13
	v_lshlrev_b32_e32 v102, 4, v139
	v_lshl_add_u32 v102, v138, 15, v102
	s_add_u32 s14, s12, 0x1000
	s_addc_u32 s15, s13, 0
	s_add_u32 s16, s12, 0x2000
	s_addc_u32 s17, s13, 0
	s_add_u32 s18, s12, 0x3000
	s_addc_u32 s19, s13, 0
	global_load_dwordx4 v[86:89], v102, s[12:13] nt
	global_load_dwordx4 v[78:81], v102, s[12:13] offset:1024 nt
	global_load_dwordx4 v[74:77], v102, s[12:13] offset:2048 nt
	global_load_dwordx4 v[62:65], v102, s[12:13] offset:3072 nt
	global_load_dwordx4 v[54:57], v102, s[14:15] nt
	global_load_dwordx4 v[38:41], v102, s[14:15] offset:1024 nt
	global_load_dwordx4 v[46:49], v102, s[14:15] offset:2048 nt
	global_load_dwordx4 v[98:101], v102, s[14:15] offset:3072 nt
	global_load_dwordx4 v[90:93], v102, s[16:17] nt
	global_load_dwordx4 v[82:85], v102, s[16:17] offset:1024 nt
	global_load_dwordx4 v[70:73], v102, s[16:17] offset:2048 nt
	global_load_dwordx4 v[66:69], v102, s[16:17] offset:3072 nt
	global_load_dwordx4 v[58:61], v102, s[18:19] nt
	global_load_dwordx4 v[50:53], v102, s[18:19] offset:1024 nt
	global_load_dwordx4 v[42:45], v102, s[18:19] offset:2048 nt
	global_load_dwordx4 v[34:37], v102, s[18:19] offset:3072 nt
	v_sub_f32_e32 v2, v4, v5
	v_cvt_f32_i32_e32 v4, v11
	v_add_f32_e32 v0, v2, v0
	v_add_f32_e32 v2, v15, v18
	v_add_f32_e32 v0, v17, v0
	v_sub_f32_e32 v3, v2, v15
	v_mul_f32_e32 v0, v14, v0
	v_sub_f32_e32 v3, v18, v3
	v_add_f32_e32 v0, v3, v0
	v_mul_f32_e32 v14, 0x3f317218, v4
	s_mov_b32 s0, 0x3f317218
	v_add_f32_e32 v3, v2, v0
	v_fma_f32 v15, v4, s0, -v14
	v_mul_f32_e32 v5, v3, v3
	v_fmac_f32_e32 v15, 0xb102e308, v4
	v_sub_f32_e32 v2, v3, v2
	v_fmamk_f32 v11, v5, 0x3e9b6dac, v234
	v_sub_f32_e32 v0, v0, v2
	v_add_f32_e32 v2, v14, v15
	v_fmaak_f32 v11, v5, v11, 0x3f2aaada
	v_sub_f32_e32 v4, v2, v14
	v_ldexp_f32 v14, v3, 1
	v_mul_f32_e32 v3, v3, v5
	v_mul_f32_e32 v3, v3, v11
	v_add_f32_e32 v5, v14, v3
	v_sub_f32_e32 v11, v5, v14
	v_ldexp_f32 v0, v0, 1
	v_sub_f32_e32 v3, v3, v11
	v_add_f32_e32 v0, v0, v3
	v_add_f32_e32 v3, v5, v0
	v_sub_f32_e32 v5, v3, v5
	v_sub_f32_e32 v0, v0, v5
	v_add_f32_e32 v5, v2, v3
	v_sub_f32_e32 v11, v5, v2
	v_sub_f32_e32 v14, v5, v11
	v_sub_f32_e32 v4, v15, v4
	v_sub_f32_e32 v2, v2, v14
	v_sub_f32_e32 v3, v3, v11
	v_add_f32_e32 v2, v3, v2
	v_add_f32_e32 v3, v4, v0
	v_sub_f32_e32 v11, v3, v4
	v_sub_f32_e32 v14, v3, v11
	v_add_f32_e32 v2, v3, v2
	v_sub_f32_e32 v4, v4, v14
	v_sub_f32_e32 v0, v0, v11
	v_add_f32_e32 v3, v5, v2
	v_add_f32_e32 v0, v0, v4
	v_sub_f32_e32 v4, v3, v5
	v_sub_f32_e32 v2, v2, v4
	v_add_f32_e32 v0, v0, v2
	v_add_f32_e32 v0, v3, v0
	v_cmp_nlt_f32_e32 vcc, 1.0, v10
	s_mov_b32 s0, 0x33800000
	v_lshl_add_u32 v14, v138, 10, 0
	v_cndmask_b32_e32 v0, v238, v0, vcc
	v_cmp_neq_f32_e32 vcc, 1.0, v10
	v_lshlrev_b32_e32 v15, 4, v139
	v_add_u32_e32 v16, v14, v15
	v_cndmask_b32_e32 v0, v239, v0, vcc
	v_cmp_gt_f32_e32 vcc, s0, v10
	s_waitcnt vmcnt(16)
; #define LAS __attribute__((address_space(3)))
; __device__ __forceinline__ float bf_lo(unsigned u) { return __uint_as_float(u << 16); }
; __device__ __forceinline__ float bf_hi(unsigned u) { return __uint_as_float(u & 0xffff0000u); }
; __device__ void sample_ret_unit(const Params& p, int l, int unit, LAS unsigned char* lds, const int tid_in) {
;     ...
;     { const int i = tid >> 6, d = (tid & 63) * 4; const bf16_t* zr = zb + (size_t)(r0 + i) * ZW + h * 256 + d;
;         const u32x2 a = *(const u32x2*)(zr + ZC_Q), kk = *(const u32x2*)(zr + ZC_K), vv = *(const u32x2*)(zr + ZC_V);
;         const float qf[4] = {bf_lo(a.x), bf_hi(a.x), bf_lo(a.y), bf_hi(a.y)}, kf[4] = {bf_lo(kk.x), bf_hi(kk.x), bf_lo(kk.y), bf_hi(kk.y)};
;         const float dk = exp2f(lg * (float)(7 - i));
;         *(LAS f32x4*)(sq + i * 256 + d) = (f32x4){qf[0], qf[1], qf[2], qf[3]};
;         *(LAS f32x4*)(sk + i * 256 + d) = (f32x4){kf[0], kf[1], kf[2], kf[3]};
;         *(LAS f32x4*)(sv + i * 256 + d) = (f32x4){bf_lo(vv.x), bf_hi(vv.x), bf_lo(vv.y), bf_hi(vv.y)};
; #pragma unroll
;         for (int j = 0; j < 4; ++j) { sqT[(d + j) * 8 + i] = qf[j]; skdT[(d + j) * 8 + i] = kf[j] * dk; } }
;     __syncthreads();
;     { const int i = wid; const f32x4 qv = *(const LAS f32x4*)(sq + i * 256 + lane * 4);
;         for (int j = 0; j < 8; ++j) { const f32x4 kv = *(const LAS f32x4*)(sk + j * 256 + lane * 4);
;             float s = wave_sum(qv[0] * kv[0] + qv[1] * kv[1] + qv[2] * kv[2] + qv[3] * kv[3]);
;             if (lane == 0) sc[i * 8 + j] = j <= i ? s * exp2f(lg * (float)(i - j)) : 0.f; } }
	v_lshlrev_b32_e32 v2, 16, v6
	v_and_b32_e32 v3, 0xffff0000, v6
	v_cndmask_b32_e64 v0, v0, -v10, vcc
	v_mul_f32_e32 v145, 0x3fb8aa3b, v0
	v_sub_u32_e32 v0, 7, v138
	v_cvt_f32_i32_e32 v0, v0
	v_lshlrev_b32_e32 v4, 16, v7
	v_and_b32_e32 v5, 0xffff0000, v7
	v_lshlrev_b32_e32 v6, 16, v8
	v_and_b32_e32 v7, 0xffff0000, v8
	v_mul_f32_e32 v8, v145, v0
	v_cmp_gt_f32_e32 vcc, s75, v8
	v_add_u32_e32 v18, 0, v15
	s_movk_i32 s0, 0xfc20
	v_cndmask_b32_e32 v8, 0, v237, vcc
	v_fmac_f32_e32 v8, v145, v0
	v_exp_f32_e32 v0, v8
	v_cndmask_b32_e32 v10, 0, v240, vcc
	v_lshlrev_b32_e32 v8, 16, v9
	v_and_b32_e32 v11, 0xffff0000, v12
	v_ldexp_f32 v0, v0, v10
	v_lshlrev_b32_e32 v10, 16, v12
	v_lshlrev_b32_e32 v12, 16, v13
	v_and_b32_e32 v13, 0xffff0000, v13
	v_and_b32_e32 v9, 0xffff0000, v9
	ds_write_b128 v16, v[2:5]
	ds_write_b128 v16, v[6:9] offset:8192
	ds_write_b128 v16, v[10:13] offset:16384
	v_lshl_add_u32 v10, v139, 5, v138
	v_lshl_add_u32 v10, v10, 2, 0
	v_add_u32_e32 v11, 0x6000, v10
	v_mul_f32_e32 v6, v0, v6
	ds_write2_b32 v11, v2, v3 offset1:8
	v_mul_f32_e32 v2, v0, v7
	v_add_u32_e32 v3, 0x8000, v10
	ds_write2_b32 v3, v6, v2 offset1:8
	v_mul_f32_e32 v2, v0, v8
	v_mul_f32_e32 v0, v0, v9
	ds_write2_b32 v11, v4, v5 offset0:16 offset1:24
	ds_write2_b32 v3, v2, v0 offset0:16 offset1:24
	s_waitcnt lgkmcnt(0)
	s_barrier
	ds_read_b128 v[2:5], v16
	ds_read_b128 v[6:9], v18 offset:8192
	v_mul_lo_u32 v0, v138, s0
	v_cmp_eq_u32_e32 vcc, 0, v139
	v_add_u32_e32 v0, v14, v0
	s_waitcnt lgkmcnt(0)
	v_mul_f32_e32 v7, v3, v7
	v_fmac_f32_e32 v7, v2, v6
	v_fmac_f32_e32 v7, v4, v8
	v_fmac_f32_e32 v7, v5, v9
	s_nop 1
	v_add_f32_dpp v6, v7, v7 quad_perm:[1,0,3,2] row_mask:0xf bank_mask:0xf bound_ctrl:1
	s_nop 1
	v_add_f32_dpp v6, v6, v6 quad_perm:[2,3,0,1] row_mask:0xf bank_mask:0xf bound_ctrl:1
	s_nop 1
	v_add_f32_dpp v6, v6, v6 row_half_mirror row_mask:0xf bank_mask:0xf bound_ctrl:1
	s_nop 1
	v_add_f32_dpp v6, v6, v6 row_mirror row_mask:0xf bank_mask:0xf bound_ctrl:1
	s_nop 0
	v_readlane_b32 s6, v6, 0
	v_readlane_b32 s10, v6, 16
	v_readlane_b32 s7, v6, 32
	v_readlane_b32 s11, v6, 48
	s_and_saveexec_b64 s[0:1], vcc
	s_cbranch_execz .LBB0_525
	v_mov_b32_e32 v6, s10
	v_mov_b32_e32 v7, s11
	v_pk_add_f32 v[6:7], s[6:7], v[6:7]
	s_nop 0
	v_add_f32_e32 v6, v6, v7
	v_cvt_f32_i32_e32 v7, v138
	v_mul_f32_e32 v8, v145, v7
	v_cmp_gt_f32_e64 s[6:7], s75, v8
	s_nop 1
	v_cndmask_b32_e64 v9, 0, v237, s[6:7]
	v_fmac_f32_e32 v9, v145, v7
	v_exp_f32_e32 v7, v9
	v_cndmask_b32_e64 v8, 0, v240, s[6:7]
	v_cmp_lt_i32_e64 s[6:7], -1, v138
	v_ldexp_f32 v7, v7, v8
	v_mul_f32_e32 v6, v7, v6
	v_cndmask_b32_e64 v6, 0, v6, s[6:7]
	ds_write_b32 v0, v6 offset:40960
